# plus: residual-norm wave sums use permlane swaps instead of two LDS bpermute round trips
# speedup vs baseline: 1.0030x; 1.0030x over previous
.LBB0_1105:
	s_ashr_i32 s7, s6, 31
	s_lshl_b64 s[40:41], s[6:7], 13
	v_lshl_add_u64 v[2:3], v[36:37], 0, s[40:41]
	global_load_dwordx4 v[10:13], v[2:3], off
	global_load_dwordx4 v[18:21], v[2:3], off offset:1024
	global_load_dwordx4 v[22:25], v[2:3], off offset:2048
	global_load_dwordx4 v[30:33], v[2:3], off offset:3072
	v_add_co_u32_e32 v2, vcc, 0x1000, v2
	s_lshl_b64 s[10:11], s[6:7], 12
	s_nop 0
	v_addc_co_u32_e32 v3, vcc, 0, v3, vcc
	v_lshl_add_u64 v[76:77], v[38:39], 0, s[10:11]
	global_load_dwordx4 v[26:29], v[2:3], off
	global_load_dwordx4 v[14:17], v[2:3], off offset:1024
	global_load_dwordx4 v[6:9], v[2:3], off offset:2048
	s_nop 0
	global_load_dwordx4 v[2:5], v[2:3], off offset:3072
	s_mov_b32 s2, 0x800000
	global_load_dwordx2 v[116:117], v[76:77], off
	global_load_dwordx2 v[118:119], v[76:77], off offset:512
	global_load_dwordx2 v[120:121], v[76:77], off offset:1024
	global_load_dwordx2 v[122:123], v[76:77], off offset:1536
	global_load_dwordx2 v[78:79], v[76:77], off offset:2048
	global_load_dwordx2 v[80:81], v[76:77], off offset:2560
	global_load_dwordx2 v[108:109], v[76:77], off offset:3072
	global_load_dwordx2 v[82:83], v[76:77], off offset:3584
	s_ashr_i32 s24, s6, 12
	s_mul_i32 s58, s24, 0x6000
	s_mul_hi_i32 s7, s24, 0x6000
	v_lshlrev_b32_e32 v43, 2, v42
	v_lshlrev_b32_e32 v45, 2, v44
	v_lshlrev_b32_e32 v47, 2, v46
	v_lshlrev_b32_e32 v49, 2, v48
	v_lshlrev_b32_e32 v53, 2, v52
	v_lshlrev_b32_e32 v57, 2, v56
	v_lshlrev_b32_e32 v61, 2, v60
	s_add_u32 s42, s54, s58
	s_addc_u32 s43, s55, s7
	s_add_u32 s42, s42, 0x4000
	s_addc_u32 s43, s43, 0
	v_lshlrev_b32_e32 v164, 2, v34
	global_load_dwordx4 v[124:127], v164, s[42:43]
	global_load_dwordx4 v[128:131], v[40:41], off
	global_load_dwordx4 v[132:135], v43, s[42:43]
	global_load_dwordx4 v[136:139], v[40:41], off offset:1024
	global_load_dwordx4 v[140:143], v45, s[42:43]
	global_load_dwordx4 v[144:147], v[40:41], off offset:2048
	global_load_dwordx4 v[148:151], v47, s[42:43]
	global_load_dwordx4 v[152:155], v[40:41], off offset:3072
	global_load_dwordx4 v[156:159], v49, s[42:43]
	global_load_dwordx4 v[160:163], v[50:51], off
	s_waitcnt vmcnt(17)
	v_lshlrev_b32_e32 v104, 16, v116
	v_and_b32_e32 v105, 0xffff0000, v116
	v_lshlrev_b32_e32 v106, 16, v117
	v_and_b32_e32 v107, 0xffff0000, v117
	v_mul_f32_e32 v0, v105, v105
	v_fmac_f32_e32 v0, v104, v104
	v_fmac_f32_e32 v0, v106, v106
	v_fmac_f32_e32 v0, v107, v107
	s_waitcnt vmcnt(16)
	v_lshlrev_b32_e32 v100, 16, v118
	v_and_b32_e32 v101, 0xffff0000, v118
	v_lshlrev_b32_e32 v102, 16, v119
	v_and_b32_e32 v103, 0xffff0000, v119
	v_mul_f32_e32 v35, v101, v101
	v_fmac_f32_e32 v35, v100, v100
	v_fmac_f32_e32 v35, v102, v102
	v_fmac_f32_e32 v35, v103, v103
	v_add_f32_e32 v0, v0, v35
	s_waitcnt vmcnt(15)
	v_lshlrev_b32_e32 v96, 16, v120
	v_and_b32_e32 v97, 0xffff0000, v120
	v_lshlrev_b32_e32 v98, 16, v121
	v_and_b32_e32 v99, 0xffff0000, v121
	v_mul_f32_e32 v35, v97, v97
	v_fmac_f32_e32 v35, v96, v96
	v_fmac_f32_e32 v35, v98, v98
	v_fmac_f32_e32 v35, v99, v99
	v_add_f32_e32 v0, v0, v35
	s_waitcnt vmcnt(14)
	v_lshlrev_b32_e32 v92, 16, v122
	v_and_b32_e32 v93, 0xffff0000, v122
	v_lshlrev_b32_e32 v94, 16, v123
	v_and_b32_e32 v95, 0xffff0000, v123
	v_mul_f32_e32 v35, v93, v93
	v_fmac_f32_e32 v35, v92, v92
	v_fmac_f32_e32 v35, v94, v94
	v_fmac_f32_e32 v35, v95, v95
	v_add_f32_e32 v0, v0, v35
	s_waitcnt vmcnt(13)
	v_and_b32_e32 v86, 0xffff0000, v78
	s_waitcnt vmcnt(12)
	v_and_b32_e32 v87, 0xffff0000, v80
	v_lshlrev_b32_e32 v85, 16, v80
	v_lshlrev_b32_e32 v84, 16, v78
	v_lshlrev_b32_e32 v88, 16, v79
	v_and_b32_e32 v90, 0xffff0000, v79
	v_pk_mul_f32 v[78:79], v[86:87], v[86:87]
	v_lshlrev_b32_e32 v89, 16, v81
	v_pk_fma_f32 v[78:79], v[84:85], v[84:85], v[78:79]
	v_and_b32_e32 v91, 0xffff0000, v81
	v_pk_fma_f32 v[78:79], v[88:89], v[88:89], v[78:79]
	s_waitcnt vmcnt(10)
	v_lshlrev_b32_e32 v77, 16, v82
	v_pk_fma_f32 v[78:79], v[90:91], v[90:91], v[78:79]
	v_lshlrev_b32_e32 v76, 16, v108
	v_add_f32_e32 v0, v0, v78
	v_add_f32_e32 v0, v0, v79
	v_and_b32_e32 v79, 0xffff0000, v82
	v_and_b32_e32 v78, 0xffff0000, v108
	v_lshlrev_b32_e32 v80, 16, v109
	v_and_b32_e32 v82, 0xffff0000, v109
	v_pk_mul_f32 v[108:109], v[78:79], v[78:79]
	v_lshlrev_b32_e32 v81, 16, v83
	v_pk_fma_f32 v[108:109], v[76:77], v[76:77], v[108:109]
	v_and_b32_e32 v83, 0xffff0000, v83
	v_pk_fma_f32 v[108:109], v[80:81], v[80:81], v[108:109]
	s_nop 0
	v_pk_fma_f32 v[108:109], v[82:83], v[82:83], v[108:109]
	s_nop 0
	v_add_f32_e32 v0, v0, v108
	v_add_f32_e32 v0, v0, v109
	s_nop 1
	v_add_f32_dpp v0, v0, v0 quad_perm:[1,0,3,2] row_mask:0xf bank_mask:0xf bound_ctrl:1
	s_nop 1
	v_add_f32_dpp v0, v0, v0 quad_perm:[2,3,0,1] row_mask:0xf bank_mask:0xf bound_ctrl:1
	s_nop 1
	v_add_f32_dpp v0, v0, v0 row_ror:4 row_mask:0xf bank_mask:0xf bound_ctrl:1
	s_nop 1
	v_add_f32_dpp v0, v0, v0 row_ror:8 row_mask:0xf bank_mask:0xf bound_ctrl:1
	v_mov_b32_e32 v35, v0
	s_nop 1
	v_permlane16_swap_b32_e32 v0, v35
	v_add_f32_e32 v0, v0, v35
	v_mov_b32_e32 v35, v0
	s_nop 1
	v_permlane32_swap_b32_e32 v0, v35
	v_add_f32_e32 v0, v0, v35
	v_fmamk_f32 v0, v0, 0x3a000000, v166
	v_cmp_gt_f32_e32 vcc, s2, v0
	v_mul_f32_e32 v35, 0x4b800000, v0
	s_add_u32 s2, s54, s58
	v_cndmask_b32_e32 v0, v0, v35, vcc
	v_rsq_f32_e32 v0, v0
	s_addc_u32 s17, s55, s7
	s_add_u32 s42, s2, 0x4000
	s_addc_u32 s43, s17, 0
	v_mul_f32_e32 v35, 0x45800000, v0
	v_cndmask_b32_e32 v0, v0, v35, vcc
	v_lshlrev_b32_e32 v35, 2, v34
	v_pk_mul_f32 v[106:107], v[106:107], v[0:1] op_sel_hi:[1,0]
	v_pk_mul_f32 v[104:105], v[104:105], v[0:1] op_sel_hi:[1,0]
	s_add_u32 s40, s84, s40
	s_addc_u32 s41, s85, s41
	v_pk_mul_f32 v[100:101], v[100:101], v[0:1] op_sel_hi:[1,0]
	v_pk_mul_f32 v[102:103], v[102:103], v[0:1] op_sel_hi:[1,0]
	v_pk_mul_f32 v[96:97], v[96:97], v[0:1] op_sel_hi:[1,0]
	v_pk_mul_f32 v[98:99], v[98:99], v[0:1] op_sel_hi:[1,0]
	v_pk_mul_f32 v[92:93], v[92:93], v[0:1] op_sel_hi:[1,0]
	v_pk_mul_f32 v[94:95], v[94:95], v[0:1] op_sel_hi:[1,0]
	s_andn2_b64 vcc, exec, s[0:1]
	s_waitcnt vmcnt(8)
	v_mov_b32_e32 v108, v124
	v_mov_b32_e32 v109, v125
	v_mov_b32_e32 v110, v126
	v_mov_b32_e32 v111, v127
	v_pk_mul_f32 v[104:105], v[108:109], v[104:105]
	v_pk_mul_f32 v[106:107], v[110:111], v[106:107]
	v_mov_b32_e32 v112, v128
	v_mov_b32_e32 v113, v129
	v_mov_b32_e32 v114, v130
	v_mov_b32_e32 v115, v131
	global_load_dwordx4 v[124:127], v53, s[42:43]
	global_load_dwordx4 v[128:131], v[54:55], off
	v_pk_fma_f32 v[10:11], v[112:113], v[104:105], v[10:11]
	v_pk_fma_f32 v[12:13], v[114:115], v[106:107], v[12:13]
	global_store_dwordx4 v35, v[10:13], s[40:41]
	s_waitcnt vmcnt(9)
	v_mov_b32_e32 v104, v132
	v_mov_b32_e32 v105, v133
	v_mov_b32_e32 v106, v134
	v_mov_b32_e32 v107, v135
	v_pk_mul_f32 v[102:103], v[106:107], v[102:103]
	v_pk_mul_f32 v[100:101], v[104:105], v[100:101]
	v_mov_b32_e32 v108, v136
	v_mov_b32_e32 v109, v137
	v_mov_b32_e32 v110, v138
	v_mov_b32_e32 v111, v139
	global_load_dwordx4 v[132:135], v57, s[42:43]
	global_load_dwordx4 v[136:139], v[58:59], off
	v_pk_fma_f32 v[20:21], v[110:111], v[102:103], v[20:21]
	v_pk_fma_f32 v[18:19], v[108:109], v[100:101], v[18:19]
	global_store_dwordx4 v35, v[18:21], s[40:41] offset:1024
	s_waitcnt vmcnt(10)
	v_mov_b32_e32 v100, v140
	v_mov_b32_e32 v101, v141
	v_mov_b32_e32 v102, v142
	v_mov_b32_e32 v103, v143
	v_pk_mul_f32 v[98:99], v[102:103], v[98:99]
	v_pk_mul_f32 v[96:97], v[100:101], v[96:97]
	v_mov_b32_e32 v104, v144
	v_mov_b32_e32 v105, v145
	v_mov_b32_e32 v106, v146
	v_mov_b32_e32 v107, v147
	global_load_dwordx4 v[140:143], v61, s[42:43]
	global_load_dwordx4 v[144:147], v[62:63], off
	v_pk_fma_f32 v[24:25], v[106:107], v[98:99], v[24:25]
	v_pk_fma_f32 v[22:23], v[104:105], v[96:97], v[22:23]
	global_store_dwordx4 v35, v[22:25], s[40:41] offset:2048
	s_waitcnt vmcnt(11)
	v_mov_b32_e32 v96, v148
	v_mov_b32_e32 v97, v149
	v_mov_b32_e32 v98, v150
	v_mov_b32_e32 v99, v151
	v_pk_mul_f32 v[94:95], v[98:99], v[94:95]
	v_pk_mul_f32 v[92:93], v[96:97], v[92:93]
	v_mov_b32_e32 v100, v152
	v_mov_b32_e32 v101, v153
	v_mov_b32_e32 v102, v154
	v_mov_b32_e32 v103, v155
	v_pk_fma_f32 v[32:33], v[102:103], v[94:95], v[32:33]
	v_pk_fma_f32 v[30:31], v[100:101], v[92:93], v[30:31]
	global_store_dwordx4 v35, v[30:33], s[40:41] offset:3072
	v_mov_b32_e32 v100, v84
	v_mov_b32_e32 v101, v86
	v_mov_b32_e32 v102, v88
	v_mov_b32_e32 v103, v90
	v_pk_mul_f32 v[100:101], v[100:101], v[0:1] op_sel_hi:[1,0]
	v_pk_mul_f32 v[102:103], v[102:103], v[0:1] op_sel_hi:[1,0]
	v_mov_b32_e32 v86, v85
	v_mov_b32_e32 v90, v89
	v_pk_mul_f32 v[84:85], v[86:87], v[0:1] op_sel_hi:[1,0]
	v_pk_mul_f32 v[86:87], v[90:91], v[0:1] op_sel_hi:[1,0]
	s_waitcnt vmcnt(10)
	v_mov_b32_e32 v92, v156
	v_mov_b32_e32 v93, v157
	v_mov_b32_e32 v94, v158
	v_mov_b32_e32 v95, v159
	v_pk_mul_f32 v[94:95], v[94:95], v[102:103]
	v_pk_mul_f32 v[92:93], v[92:93], v[100:101]
	v_mov_b32_e32 v96, v160
	v_mov_b32_e32 v97, v161
	v_mov_b32_e32 v98, v162
	v_mov_b32_e32 v99, v163
	v_pk_fma_f32 v[28:29], v[98:99], v[94:95], v[28:29]
	v_pk_fma_f32 v[26:27], v[96:97], v[92:93], v[26:27]
	global_store_dwordx4 v49, v[26:29], s[40:41]
	s_waitcnt vmcnt(9)
	v_mov_b32_e32 v92, v124
	v_mov_b32_e32 v93, v125
	v_mov_b32_e32 v94, v126
	v_mov_b32_e32 v95, v127
	v_pk_mul_f32 v[86:87], v[94:95], v[86:87]
	v_pk_mul_f32 v[84:85], v[92:93], v[84:85]
	v_mov_b32_e32 v96, v128
	v_mov_b32_e32 v97, v129
	v_mov_b32_e32 v98, v130
	v_mov_b32_e32 v99, v131
	v_pk_fma_f32 v[16:17], v[98:99], v[86:87], v[16:17]
	v_pk_fma_f32 v[14:15], v[96:97], v[84:85], v[14:15]
	global_store_dwordx4 v53, v[14:17], s[40:41]
	v_mov_b32_e32 v92, v76
	v_mov_b32_e32 v93, v78
	v_mov_b32_e32 v94, v80
	v_mov_b32_e32 v95, v82
	v_pk_mul_f32 v[92:93], v[92:93], v[0:1] op_sel_hi:[1,0]
	v_pk_mul_f32 v[94:95], v[94:95], v[0:1] op_sel_hi:[1,0]
	v_mov_b32_e32 v78, v77
	v_mov_b32_e32 v82, v81
	v_pk_mul_f32 v[76:77], v[78:79], v[0:1] op_sel_hi:[1,0]
	v_pk_mul_f32 v[78:79], v[82:83], v[0:1] op_sel_hi:[1,0]
	s_waitcnt vmcnt(7)
	v_mov_b32_e32 v84, v132
	v_mov_b32_e32 v85, v133
	v_mov_b32_e32 v86, v134
	v_mov_b32_e32 v87, v135
	v_pk_mul_f32 v[86:87], v[94:95], v[86:87]
	v_pk_mul_f32 v[84:85], v[92:93], v[84:85]
	v_mov_b32_e32 v88, v136
	v_mov_b32_e32 v89, v137
	v_mov_b32_e32 v90, v138
	v_mov_b32_e32 v91, v139
	v_pk_fma_f32 v[8:9], v[90:91], v[86:87], v[8:9]
	v_pk_fma_f32 v[6:7], v[88:89], v[84:85], v[6:7]
	global_store_dwordx4 v57, v[6:9], s[40:41]
	s_waitcnt vmcnt(5)
	v_mov_b32_e32 v84, v140
	v_mov_b32_e32 v85, v141
	v_mov_b32_e32 v86, v142
	v_mov_b32_e32 v87, v143
	v_pk_mul_f32 v[78:79], v[78:79], v[86:87]
	v_pk_mul_f32 v[76:77], v[76:77], v[84:85]
	v_mov_b32_e32 v88, v144
	v_mov_b32_e32 v89, v145
	v_mov_b32_e32 v90, v146
	v_mov_b32_e32 v91, v147
	v_pk_fma_f32 v[4:5], v[90:91], v[78:79], v[4:5]
	v_pk_fma_f32 v[2:3], v[88:89], v[76:77], v[2:3]
	global_store_dwordx4 v61, v[2:5], s[40:41]
	s_cbranch_vccnz .LBB0_1104
	v_mul_f32_e32 v0, v11, v11
	v_mul_f32_e32 v76, v19, v19
	v_fmac_f32_e32 v0, v10, v10
	v_fmac_f32_e32 v76, v18, v18
	v_fmac_f32_e32 v0, v12, v12
	v_fmac_f32_e32 v76, v20, v20
	v_fmac_f32_e32 v0, v13, v13
	v_fmac_f32_e32 v76, v21, v21
	v_add_f32_e32 v0, v0, v76
	v_mul_f32_e32 v76, v23, v23
	v_fmac_f32_e32 v76, v22, v22
	v_fmac_f32_e32 v76, v24, v24
	v_fmac_f32_e32 v76, v25, v25
	v_add_f32_e32 v0, v76, v0
	v_mul_f32_e32 v76, v31, v31
	v_fmac_f32_e32 v76, v30, v30
	v_fmac_f32_e32 v76, v32, v32
	v_fmac_f32_e32 v76, v33, v33
	v_mov_b32_e32 v78, v15
	v_mov_b32_e32 v79, v27
	v_add_f32_e32 v0, v76, v0
	v_mov_b32_e32 v76, v14
	v_mov_b32_e32 v77, v26
	v_pk_mul_f32 v[78:79], v[78:79], v[78:79]
	s_mov_b32 s2, 0x800000
	v_pk_fma_f32 v[76:77], v[76:77], v[76:77], v[78:79]
	v_mov_b32_e32 v78, v16
	v_mov_b32_e32 v79, v28
	v_pk_fma_f32 v[76:77], v[78:79], v[78:79], v[76:77]
	v_mov_b32_e32 v78, v17
	v_mov_b32_e32 v79, v29
	v_pk_fma_f32 v[76:77], v[78:79], v[78:79], v[76:77]
	v_mov_b32_e32 v78, v3
	v_add_f32_e32 v0, v77, v0
	v_mov_b32_e32 v79, v7
	v_add_f32_e32 v0, v76, v0
	v_mov_b32_e32 v76, v2
	v_mov_b32_e32 v77, v6
	v_pk_mul_f32 v[78:79], v[78:79], v[78:79]
	s_add_u32 s42, s62, s58
	v_pk_fma_f32 v[76:77], v[76:77], v[76:77], v[78:79]
	v_mov_b32_e32 v78, v4
	v_mov_b32_e32 v79, v8
	v_pk_fma_f32 v[76:77], v[78:79], v[78:79], v[76:77]
	v_mov_b32_e32 v78, v5
	v_mov_b32_e32 v79, v9
	v_pk_fma_f32 v[76:77], v[78:79], v[78:79], v[76:77]
	s_addc_u32 s43, s63, s7
	v_add_f32_e32 v0, v77, v0
	v_add_f32_e32 v0, v76, v0
	s_add_u32 s40, s42, 0x2000
	s_addc_u32 s41, s43, 0
	v_add_f32_dpp v0, v0, v0 quad_perm:[1,0,3,2] row_mask:0xf bank_mask:0xf bound_ctrl:1
	s_nop 1
	v_add_f32_dpp v0, v0, v0 quad_perm:[2,3,0,1] row_mask:0xf bank_mask:0xf bound_ctrl:1
	s_nop 1
	v_add_f32_dpp v0, v0, v0 row_ror:4 row_mask:0xf bank_mask:0xf bound_ctrl:1
	s_nop 1
	v_add_f32_dpp v0, v0, v0 row_ror:8 row_mask:0xf bank_mask:0xf bound_ctrl:1
	v_mov_b32_e32 v76, v0
	s_nop 1
	v_permlane16_swap_b32_e32 v0, v76
	v_add_f32_e32 v0, v0, v76
	v_mov_b32_e32 v76, v0
	s_nop 1
	v_permlane32_swap_b32_e32 v0, v76
	v_add_f32_e32 v0, v0, v76
	v_fmamk_f32 v0, v0, 0x3a000000, v166
	v_cmp_gt_f32_e32 vcc, s2, v0
	v_mul_f32_e32 v76, 0x4b800000, v0
	s_nop 0
	v_cndmask_b32_e32 v0, v0, v76, vcc
	v_rsq_f32_e32 v0, v0
	s_nop 0
	v_mul_f32_e32 v76, 0x45800000, v0
	v_cndmask_b32_e32 v0, v0, v76, vcc
	global_load_dwordx4 v[76:79], v[64:65], off
	global_load_dwordx4 v[80:83], v35, s[42:43]
	global_load_dwordx4 v[84:87], v35, s[40:41]
	v_pk_mul_f32 v[12:13], v[12:13], v[0:1] op_sel_hi:[1,0]
	v_pk_mul_f32 v[10:11], v[10:11], v[0:1] op_sel_hi:[1,0]
	v_pk_mul_f32 v[18:19], v[18:19], v[0:1] op_sel_hi:[1,0]
	v_pk_mul_f32 v[22:23], v[22:23], v[0:1] op_sel_hi:[1,0]
	v_pk_mul_f32 v[30:31], v[30:31], v[0:1] op_sel_hi:[1,0]
	v_pk_mul_f32 v[26:27], v[26:27], v[0:1] op_sel_hi:[1,0]
	v_pk_mul_f32 v[14:15], v[14:15], v[0:1] op_sel_hi:[1,0]
	v_pk_mul_f32 v[8:9], v[8:9], v[0:1] op_sel_hi:[1,0]
	v_pk_mul_f32 v[6:7], v[6:7], v[0:1] op_sel_hi:[1,0]
	v_pk_mul_f32 v[4:5], v[4:5], v[0:1] op_sel_hi:[1,0]
	v_pk_mul_f32 v[2:3], v[2:3], v[0:1] op_sel_hi:[1,0]
	s_waitcnt vmcnt(2)
	v_pk_mul_f32 v[10:11], v[76:77], v[10:11]
	v_pk_mul_f32 v[12:13], v[78:79], v[12:13]
	s_waitcnt vmcnt(0)
	v_pk_add_f32 v[76:77], v[86:87], 1.0 op_sel_hi:[1,0]
	v_pk_add_f32 v[78:79], v[84:85], 1.0 op_sel_hi:[1,0]
	v_pk_fma_f32 v[12:13], v[76:77], v[12:13], v[82:83]
	v_pk_fma_f32 v[10:11], v[78:79], v[10:11], v[80:81]
	s_nop 0
	v_cvt_pk_bf16_f32 v10, v10, v11
	v_cvt_pk_bf16_f32 v11, v12, v13
	v_lshl_add_u64 v[12:13], v[74:75], 0, s[10:11]
	global_store_dwordx2 v[12:13], v[10:11], off
	global_load_dwordx4 v[76:79], v[64:65], off offset:1024
	global_load_dwordx4 v[80:83], v35, s[42:43] offset:1024
	global_load_dwordx4 v[84:87], v43, s[40:41]
	v_pk_mul_f32 v[10:11], v[20:21], v[0:1] op_sel_hi:[1,0]
	s_waitcnt vmcnt(2)
	v_pk_mul_f32 v[18:19], v[76:77], v[18:19]
	v_pk_mul_f32 v[10:11], v[78:79], v[10:11]
	s_waitcnt vmcnt(0)
	v_pk_add_f32 v[20:21], v[86:87], 1.0 op_sel_hi:[1,0]
	v_pk_add_f32 v[76:77], v[84:85], 1.0 op_sel_hi:[1,0]
	v_pk_fma_f32 v[10:11], v[20:21], v[10:11], v[82:83]
	v_pk_fma_f32 v[18:19], v[76:77], v[18:19], v[80:81]
	s_nop 0
	v_cvt_pk_bf16_f32 v18, v18, v19
	v_cvt_pk_bf16_f32 v19, v10, v11
	global_store_dwordx2 v[12:13], v[18:19], off offset:512
	global_load_dwordx4 v[18:21], v[64:65], off offset:2048
	s_nop 0
	global_load_dwordx4 v[76:79], v35, s[42:43] offset:2048
	global_load_dwordx4 v[80:83], v45, s[40:41]
	v_pk_mul_f32 v[10:11], v[24:25], v[0:1] op_sel_hi:[1,0]
	s_waitcnt vmcnt(2)
	v_pk_mul_f32 v[18:19], v[18:19], v[22:23]
	v_pk_mul_f32 v[10:11], v[20:21], v[10:11]
	s_waitcnt vmcnt(0)
	v_pk_add_f32 v[20:21], v[82:83], 1.0 op_sel_hi:[1,0]
	v_pk_add_f32 v[22:23], v[80:81], 1.0 op_sel_hi:[1,0]
	v_pk_fma_f32 v[10:11], v[20:21], v[10:11], v[78:79]
	v_pk_fma_f32 v[18:19], v[22:23], v[18:19], v[76:77]
	s_nop 0
	v_cvt_pk_bf16_f32 v18, v18, v19
	v_cvt_pk_bf16_f32 v19, v10, v11
	global_store_dwordx2 v[12:13], v[18:19], off offset:1024
	global_load_dwordx4 v[18:21], v[64:65], off offset:3072
	s_nop 0
	global_load_dwordx4 v[22:25], v35, s[42:43] offset:3072
	global_load_dwordx4 v[76:79], v47, s[40:41]
	v_pk_mul_f32 v[10:11], v[32:33], v[0:1] op_sel_hi:[1,0]
	s_waitcnt vmcnt(2)
	v_pk_mul_f32 v[18:19], v[30:31], v[18:19]
	v_pk_mul_f32 v[10:11], v[10:11], v[20:21]
	s_waitcnt vmcnt(0)
	v_pk_add_f32 v[20:21], v[78:79], 1.0 op_sel_hi:[1,0]
	v_pk_add_f32 v[30:31], v[76:77], 1.0 op_sel_hi:[1,0]
	v_pk_fma_f32 v[10:11], v[10:11], v[20:21], v[24:25]
	v_pk_fma_f32 v[18:19], v[18:19], v[30:31], v[22:23]
	s_nop 0
	v_cvt_pk_bf16_f32 v18, v18, v19
	v_cvt_pk_bf16_f32 v19, v10, v11
	global_store_dwordx2 v[12:13], v[18:19], off offset:1536
	global_load_dwordx4 v[18:21], v[66:67], off
	s_nop 0
	global_load_dwordx4 v[22:25], v49, s[42:43]
	global_load_dwordx4 v[30:33], v49, s[40:41]
	v_pk_mul_f32 v[10:11], v[28:29], v[0:1] op_sel_hi:[1,0]
	s_waitcnt vmcnt(2)
	v_pk_mul_f32 v[18:19], v[26:27], v[18:19]
	v_pk_mul_f32 v[10:11], v[10:11], v[20:21]
	s_waitcnt vmcnt(0)
	v_pk_add_f32 v[20:21], v[32:33], 1.0 op_sel_hi:[1,0]
	v_pk_add_f32 v[26:27], v[30:31], 1.0 op_sel_hi:[1,0]
	v_pk_fma_f32 v[10:11], v[10:11], v[20:21], v[24:25]
	v_pk_fma_f32 v[18:19], v[18:19], v[26:27], v[22:23]
	s_nop 0
	v_cvt_pk_bf16_f32 v18, v18, v19
	v_cvt_pk_bf16_f32 v19, v10, v11
	global_store_dwordx2 v[12:13], v[18:19], off offset:2048
	global_load_dwordx4 v[18:21], v[68:69], off
	s_nop 0
	global_load_dwordx4 v[22:25], v53, s[42:43]
	global_load_dwordx4 v[26:29], v53, s[40:41]
	v_pk_mul_f32 v[10:11], v[16:17], v[0:1] op_sel_hi:[1,0]
	s_waitcnt vmcnt(2)
	v_pk_mul_f32 v[14:15], v[14:15], v[18:19]
	v_pk_mul_f32 v[10:11], v[10:11], v[20:21]
	s_waitcnt vmcnt(0)
	v_pk_add_f32 v[16:17], v[28:29], 1.0 op_sel_hi:[1,0]
	v_pk_add_f32 v[18:19], v[26:27], 1.0 op_sel_hi:[1,0]
	v_pk_fma_f32 v[10:11], v[10:11], v[16:17], v[24:25]
	v_pk_fma_f32 v[14:15], v[14:15], v[18:19], v[22:23]
	s_nop 0
	v_cvt_pk_bf16_f32 v14, v14, v15
	v_cvt_pk_bf16_f32 v15, v10, v11
	global_store_dwordx2 v[12:13], v[14:15], off offset:2560
	global_load_dwordx4 v[14:17], v[70:71], off
	s_nop 0
	global_load_dwordx4 v[18:21], v57, s[42:43]
	global_load_dwordx4 v[22:25], v57, s[40:41]
	s_waitcnt vmcnt(2)
	v_pk_mul_f32 v[6:7], v[6:7], v[14:15]
	v_pk_mul_f32 v[8:9], v[8:9], v[16:17]
	s_waitcnt vmcnt(0)
	v_pk_add_f32 v[10:11], v[24:25], 1.0 op_sel_hi:[1,0]
	v_pk_add_f32 v[14:15], v[22:23], 1.0 op_sel_hi:[1,0]
	v_pk_fma_f32 v[8:9], v[8:9], v[10:11], v[20:21]
	v_pk_fma_f32 v[6:7], v[6:7], v[14:15], v[18:19]
	s_nop 0
	v_cvt_pk_bf16_f32 v6, v6, v7
	v_cvt_pk_bf16_f32 v7, v8, v9
	global_store_dwordx2 v[12:13], v[6:7], off offset:3072
	global_load_dwordx4 v[6:9], v[72:73], off
	s_nop 0
	global_load_dwordx4 v[14:17], v61, s[42:43]
	global_load_dwordx4 v[18:21], v61, s[40:41]
	s_waitcnt vmcnt(2)
	v_pk_mul_f32 v[2:3], v[2:3], v[6:7]
	v_pk_mul_f32 v[4:5], v[4:5], v[8:9]
	s_waitcnt vmcnt(0)
	v_pk_add_f32 v[6:7], v[20:21], 1.0 op_sel_hi:[1,0]
	v_pk_add_f32 v[8:9], v[18:19], 1.0 op_sel_hi:[1,0]
	v_pk_fma_f32 v[4:5], v[4:5], v[6:7], v[16:17]
	v_pk_fma_f32 v[2:3], v[2:3], v[8:9], v[14:15]
	s_nop 0
	v_cvt_pk_bf16_f32 v2, v2, v3
	v_cvt_pk_bf16_f32 v3, v4, v5
	global_store_dwordx2 v[12:13], v[2:3], off offset:3584
	s_branch .LBB0_1104
